# MLA main loop: running max folded into QK accumulator init (removes 32 v_sub per tile); on top of v13 GEMM schedule
# baseline (speedup 1.0000x reference)
; DI int get_tid() { int t = threadIdx.x; asm volatile("" : "+v"(t)); return t; }
; template <int DK, int MODE> ...
;     ...
;   const int tid = get_tid(), lane = tid & 63, wave = __builtin_amdgcn_readfirstlane(tid >> 6), l32 = lane & 31, h = lane >> 5;
;   const int tq0 = qb * 128 + 32 * wave;
;   const int qpos = tq0 + l32;
;   bf16x8 qf[NKS];
;   {
;     const bf16_t* qp = Q + (size_t)qpos * DK + h * 8;
; #pragma unroll
;     for (int ks = 0; ks < NKS; ++ks) qf[ks] = *(const bf16x8*)(qp + ks * 16);
; #pragma unroll
;     for (int ks = 0; ks < NKS; ++ks) asm volatile("" : "+v"(qf[ks]));
;   }
;   float Fref = 0.f;
;   if (MODE == 1) Fref = F[qb * 128];
;   f32x16 o0, o1;
; #pragma unroll
;   for (int e = 0; e < 16; ++e) { o0[e] = 0.f; o1[e] = 0.f; }
;   float m = -1e30f, lsum = 0.f, R = 1.f;
;     ...
;   gload(ASC ? start : ntiles - 1);
;   swrite(0);
;   __syncthreads();
.LBB0_522:
	s_and_b64 s[0:1], s[56:57], exec
	s_cselect_b32 s0, s63, s64
	s_and_b64 vcc, exec, s[48:49]
	s_mov_b64 s[4:5], -1
	s_cbranch_vccz .LBB0_541
	s_load_dwordx2 s[20:21], s[18:19], 0x110
	s_load_dwordx4 s[8:11], s[18:19], 0x100
	v_mov_b32_e32 v36, v188
	s_load_dwordx4 s[4:7], s[18:19], 0x90
	v_mov_b32_e32 v161, v1
	s_waitcnt lgkmcnt(0)
	s_add_u32 s12, s8, s52
	s_addc_u32 s13, s9, s53
	s_add_u32 s22, s10, s52
	s_addc_u32 s23, s11, s53
	s_add_u32 s8, s20, s50
	v_readfirstlane_b32 s1, v36
	s_addc_u32 s9, s21, s51
	s_ashr_i32 s1, s1, 1
	s_lshl_b32 s2, s0, 7
	s_andn2_b32 s1, s1, 31
	v_and_b32_e32 v37, 31, v36
	s_add_i32 s1, s1, s2
	v_bfe_u32 v38, v36, 5, 1
	v_or_b32_e32 v152, s1, v37
	s_waitcnt vmcnt(7)
	v_mov_b64_e32 v[2:3], s[12:13]
	v_mad_i64_i32 v[2:3], s[12:13], v152, s78, v[2:3]
	v_lshlrev_b32_e32 v0, 4, v38
	v_lshl_add_u64 v[2:3], v[2:3], 0, v[0:1]
	global_load_dwordx4 v[80:83], v[2:3], off
	global_load_dwordx4 v[128:131], v[2:3], off offset:32
	global_load_dwordx4 v[124:127], v[2:3], off offset:64
	global_load_dwordx4 v[120:123], v[2:3], off offset:96
	global_load_dwordx4 v[116:119], v[2:3], off offset:128
	global_load_dwordx4 v[112:115], v[2:3], off offset:160
	v_mul_hi_i32 v2, v36, s69
	v_lshrrev_b32_e32 v3, 31, v2
	v_ashrrev_i32_e32 v2, 1, v2
	s_waitcnt vmcnt(7)
	v_add_u32_e32 v28, 0x100, v36
	v_add_u32_e32 v39, v2, v3
	v_mul_hi_i32 v6, v28, s69
	v_mul_lo_u32 v2, v39, 12
	v_lshrrev_b32_e32 v7, 31, v6
	v_ashrrev_i32_e32 v6, 1, v6
	v_add_u32_e32 v12, 0x200, v36
	v_sub_u32_e32 v40, v36, v2
	v_add_u32_e32 v41, v6, v7
	v_mul_hi_i32 v13, v12, s69
	v_lshlrev_b32_e32 v154, 3, v40
	v_mul_lo_u32 v6, v41, 12
	v_lshrrev_b32_e32 v18, 31, v13
	v_ashrrev_i32_e32 v13, 1, v13
	v_mov_b64_e32 v[10:11], s[22:23]
	v_ashrrev_i32_e32 v155, 31, v154
	v_sub_u32_e32 v42, v28, v6
	v_add_u32_e32 v43, v13, v18
	v_mad_i64_i32 v[2:3], s[12:13], v39, s78, v[10:11]
	v_lshlrev_b64 v[14:15], 1, v[154:155]
	v_lshlrev_b32_e32 v156, 3, v42
	v_mul_lo_u32 v13, v43, 12
	v_lshl_add_u64 v[2:3], v[2:3], 0, v[14:15]
	v_ashrrev_i32_e32 v157, 31, v156
	v_sub_u32_e32 v44, v12, v13
	v_ashrrev_i32_e32 v22, 3, v36
	v_mad_i64_i32 v[6:7], s[12:13], v41, s78, v[10:11]
	v_lshlrev_b64 v[16:17], 1, v[156:157]
	v_lshlrev_b32_e32 v158, 3, v44
	v_ashrrev_i32_e32 v23, 31, v22
	v_lshl_add_u64 v[6:7], v[6:7], 0, v[16:17]
	v_ashrrev_i32_e32 v159, 31, v158
	v_lshlrev_b64 v[20:21], 14, v[22:23]
	v_lshlrev_b32_e32 v23, 3, v36
	s_waitcnt vmcnt(6)
	v_ashrrev_i32_e32 v32, 3, v28
	v_mad_i64_i32 v[10:11], s[12:13], v43, s78, v[10:11]
	v_lshlrev_b64 v[18:19], 1, v[158:159]
	v_and_b32_e32 v23, 56, v23
	v_ashrrev_i32_e32 v33, 31, v32
	v_lshl_add_u64 v[10:11], v[10:11], 0, v[18:19]
	v_lshl_add_u64 v[24:25], s[8:9], 0, v[20:21]
	v_lshlrev_b32_e32 v160, 1, v23
	v_lshlrev_b64 v[34:35], 14, v[32:33]
	v_lshl_add_u64 v[24:25], v[24:25], 0, v[160:161]
	v_lshl_add_u64 v[28:29], s[8:9], 0, v[34:35]
	v_lshl_add_u64 v[28:29], v[28:29], 0, v[160:161]
	v_mul_lo_u32 v159, v39, s70
	v_lshlrev_b32_e32 v23, 4, v40
	v_lshl_add_u32 v23, v159, 1, v23
	v_mul_lo_u32 v161, v41, s70
	s_or_b32 s8, s1, 31
	s_movk_i32 s9, 0xd0
	s_or_b32 s2, s2, 64
	v_mad_u32_u24 v175, v37, s9, v0
	s_add_u32 s9, s20, s44
	v_mul_lo_u32 v172, v43, s70
	v_lshlrev_b32_e32 v0, 6, v37
	s_addc_u32 s13, s21, s45
	v_mul_lo_u32 v173, v22, s33
	v_sub_u32_e32 v157, v175, v0
	s_waitcnt vmcnt(5)
	s_waitcnt vmcnt(4)
	s_waitcnt vmcnt(3)
	s_waitcnt vmcnt(2)
	s_waitcnt vmcnt(1)
	s_waitcnt vmcnt(0)
	global_load_dwordx4 v[2:5], v[2:3], off
	s_add_u32 s12, s9, 0x80
	global_load_dwordx4 v[6:9], v[6:7], off
	v_lshlrev_b32_e32 v0, 4, v36
	global_load_dwordx4 v[10:13], v[10:11], off
	v_mul_lo_u32 v174, v32, s33
	global_load_dwordx4 v[24:27], v[24:25], off
	s_addc_u32 s13, s13, 0
	global_load_dwordx4 v[28:31], v[28:29], off
	v_and_b32_e32 v0, 0x70, v0
	v_or_b32_e32 v34, v34, v0
	v_or_b32_e32 v20, v20, v0
	s_add_u32 s10, s10, 0x3000
	v_lshl_add_u64 v[162:163], s[12:13], 0, v[34:35]
	v_lshl_add_u64 v[164:165], s[12:13], 0, v[20:21]
	s_addc_u32 s11, s11, 0
	v_lshlrev_b32_e32 v149, 2, v38
	v_mov_b32_e32 v0, v1
	v_ashrrev_i32_e32 v153, 31, v152
	s_mov_b32 s9, 0
	v_mov_b32_e32 v155, 0
	v_mov_b32_e32 v216, 0
	v_mov_b32_e32 v217, 0
	v_mov_b32_e32 v218, 0
	v_mov_b32_e32 v219, 0
	v_mov_b32_e32 v220, 0
	v_mov_b32_e32 v221, 0
	v_mov_b32_e32 v222, 0
	v_mov_b32_e32 v223, 0
	v_mov_b32_e32 v224, 0
	v_mov_b32_e32 v225, 0
	v_mov_b32_e32 v226, 0
	v_mov_b32_e32 v227, 0
	v_mov_b32_e32 v228, 0
	v_mov_b32_e32 v229, 0
	v_mov_b32_e32 v230, 0
	v_mov_b32_e32 v231, 0
	v_mov_b32_e32 v151, 0
	s_waitcnt vmcnt(4)
	ds_write_b128 v23, v[2:5]
	v_lshlrev_b32_e32 v2, 4, v42
	v_lshl_add_u32 v2, v161, 1, v2
	s_waitcnt vmcnt(3)
	ds_write_b128 v2, v[6:9]
	v_lshlrev_b32_e32 v2, 4, v44
	v_lshl_add_u32 v2, v172, 1, v2
	s_waitcnt vmcnt(2)
	ds_write_b128 v2, v[10:13]
	v_lshl_add_u32 v2, v173, 1, v160
	s_waitcnt vmcnt(1)
	ds_write_b128 v2, v[24:27] offset:26624
	v_lshl_add_u32 v2, v174, 1, v160
	s_waitcnt vmcnt(0)
	ds_write_b128 v2, v[28:31] offset:26624
	v_mad_i64_i32 v[2:3], s[12:13], v43, s78, v[18:19]
	v_lshl_add_u64 v[166:167], s[10:11], 0, v[2:3]
	v_mad_i64_i32 v[2:3], s[12:13], v41, s78, v[16:17]
	v_lshl_add_u64 v[168:169], s[10:11], 0, v[2:3]
	v_mad_i64_i32 v[2:3], s[12:13], v39, s78, v[14:15]
	v_mov_b32_e32 v14, v1
	v_mov_b32_e32 v15, v1
	v_lshl_add_u64 v[170:171], s[10:11], 0, v[2:3]
	v_mov_b32_e32 v2, v1
	v_mov_b32_e32 v3, v1
	v_mov_b32_e32 v4, v1
	v_mov_b32_e32 v5, v1
	v_mov_b32_e32 v6, v1
	v_mov_b32_e32 v7, v1
	v_mov_b32_e32 v8, v1
	v_mov_b32_e32 v9, v1
	v_mov_b32_e32 v10, v1
	v_mov_b32_e32 v11, v1
	v_mov_b32_e32 v12, v1
	v_mov_b32_e32 v13, v1
	v_mov_b64_e32 v[30:31], v[14:15]
	v_mov_b64_e32 v[46:47], v[14:15]
	s_mov_b32 s10, 0
	v_mov_b64_e32 v[28:29], v[12:13]
	v_mov_b64_e32 v[26:27], v[10:11]
	v_mov_b64_e32 v[24:25], v[8:9]
	v_mov_b64_e32 v[22:23], v[6:7]
	v_mov_b64_e32 v[20:21], v[4:5]
	v_mov_b64_e32 v[18:19], v[2:3]
	v_mov_b64_e32 v[16:17], v[0:1]
	v_mov_b64_e32 v[44:45], v[12:13]
	v_mov_b64_e32 v[42:43], v[10:11]
	v_mov_b64_e32 v[40:41], v[8:9]
	v_mov_b64_e32 v[38:39], v[6:7]
	v_mov_b64_e32 v[36:37], v[4:5]
	v_mov_b64_e32 v[34:35], v[2:3]
	v_mov_b64_e32 v[32:33], v[0:1]
	s_waitcnt lgkmcnt(0)
	s_barrier
	s_branch .LBB0_526
; #define MFMA(a, b, c) __builtin_amdgcn_mfma_f32_32x32x16_bf16((a), (b), (c), 0, 0, 0)
; DI unsigned pack2(float a, float b) { f32x2 v = {a, b}; return __builtin_bit_cast(unsigned, __builtin_convertvector(v, bf16v2)); }
; template <int DK, int MODE> ...
;     ...
;         float ps0 = 0.f, ps1 = 0.f, ps2 = 0.f, ps3 = 0.f;
; #pragma unroll
;         for (int e = 0; e < 16; e += 4) {
;           s0[e] = __builtin_amdgcn_exp2f(s0[e] - m); s0[e + 1] = __builtin_amdgcn_exp2f(s0[e + 1] - m); s0[e + 2] = __builtin_amdgcn_exp2f(s0[e + 2] - m); s0[e + 3] = __builtin_amdgcn_exp2f(s0[e + 3] - m);
;           ps0 += s0[e]; ps1 += s0[e + 1]; ps2 += s0[e + 2]; ps3 += s0[e + 3];
;         }
; #pragma unroll
;         for (int e = 0; e < 16; e += 4) {
;           s1[e] = __builtin_amdgcn_exp2f(s1[e] - m); s1[e + 1] = __builtin_amdgcn_exp2f(s1[e + 1] - m); s1[e + 2] = __builtin_amdgcn_exp2f(s1[e + 2] - m); s1[e + 3] = __builtin_amdgcn_exp2f(s1[e + 3] - m);
;           ps0 += s1[e]; ps1 += s1[e + 1]; ps2 += s1[e + 2]; ps3 += s1[e + 3];
;         }
;         lsum += (ps0 + ps1) + (ps2 + ps3);
;     ...
; #pragma unroll
;       for (int j = 0; j < 2; ++j) {
;         u32x4 a, b;
;         a.x = pack2(s0[8 * j], s0[8 * j + 1]); a.y = pack2(s0[8 * j + 2], s0[8 * j + 3]); a.z = pack2(s0[8 * j + 4], s0[8 * j + 5]); a.w = pack2(s0[8 * j + 6], s0[8 * j + 7]);
;         b.x = pack2(s1[8 * j], s1[8 * j + 1]); b.y = pack2(s1[8 * j + 2], s1[8 * j + 3]); b.z = pack2(s1[8 * j + 4], s1[8 * j + 5]); b.w = pack2(s1[8 * j + 6], s1[8 * j + 7]);
;         pf[j] = __builtin_bit_cast(bf16x8, a); pf[2 + j] = __builtin_bit_cast(bf16x8, b);
;       }
;       __builtin_amdgcn_s_setprio(1);
; #pragma unroll
;       for (int j = 0; j < 4; ++j) { o0 = MFMA(vf0[j], pf[j], o0); o1 = MFMA(vf1[j], pf[j], o1); }
;       __builtin_amdgcn_s_setprio(0);
.LBB0_524:
	v_exp_f32_e32 v14, v64
	v_exp_f32_e32 v64, v65
	v_exp_f32_e32 v15, v66
	v_exp_f32_e32 v65, v67
	v_exp_f32_e32 v66, v68
	v_exp_f32_e32 v68, v69
	v_exp_f32_e32 v67, v70
	v_exp_f32_e32 v69, v71
	v_exp_f32_e32 v70, v72
	v_exp_f32_e32 v72, v73
	v_exp_f32_e32 v71, v74
	v_exp_f32_e32 v73, v75
	v_exp_f32_e32 v74, v76
	v_exp_f32_e32 v76, v77
	v_exp_f32_e32 v75, v78
	v_exp_f32_e32 v77, v79
	v_exp_f32_e32 v78, v48
	v_exp_f32_e32 v176, v49
	v_exp_f32_e32 v79, v50
	v_exp_f32_e32 v177, v51
	v_exp_f32_e32 v178, v52
	v_exp_f32_e32 v180, v53
	v_exp_f32_e32 v179, v54
	v_exp_f32_e32 v181, v55
	v_exp_f32_e32 v182, v56
	v_exp_f32_e32 v184, v57
	v_exp_f32_e32 v183, v58
	v_exp_f32_e32 v185, v59
	v_exp_f32_e32 v186, v60
	v_pk_add_f32 v[48:49], v[14:15], 0 op_sel_hi:[1,0]
	v_pk_add_f32 v[50:51], v[64:65], 0 op_sel_hi:[1,0]
	v_exp_f32_e32 v200, v61
	v_pk_add_f32 v[48:49], v[66:67], v[48:49]
	v_pk_add_f32 v[50:51], v[68:69], v[50:51]
	v_exp_f32_e32 v187, v62
	v_pk_add_f32 v[48:49], v[70:71], v[48:49]
	v_pk_add_f32 v[50:51], v[72:73], v[50:51]
	v_exp_f32_e32 v201, v63
	v_pk_add_f32 v[202:203], v[74:75], v[48:49]
	v_pk_add_f32 v[204:205], v[76:77], v[50:51]
	v_cvt_pk_bf16_f32 v48, v14, v64
	v_cvt_pk_bf16_f32 v49, v15, v65
	v_pk_add_f32 v[14:15], v[78:79], v[202:203]
	v_pk_add_f32 v[64:65], v[176:177], v[204:205]
	v_pk_add_f32 v[14:15], v[178:179], v[14:15]
	v_pk_add_f32 v[64:65], v[180:181], v[64:65]
	v_pk_add_f32 v[14:15], v[182:183], v[14:15]
	v_pk_add_f32 v[64:65], v[184:185], v[64:65]
	v_pk_add_f32 v[14:15], v[186:187], v[14:15]
	v_pk_add_f32 v[64:65], v[200:201], v[64:65]
	v_cvt_pk_bf16_f32 v50, v66, v68
	v_pk_add_f32 v[14:15], v[14:15], v[64:65]
	v_cvt_pk_bf16_f32 v51, v67, v69
	v_cvt_pk_bf16_f32 v52, v78, v176
	v_cvt_pk_bf16_f32 v53, v79, v177
	v_cvt_pk_bf16_f32 v54, v178, v180
	v_cvt_pk_bf16_f32 v55, v179, v181
	v_cvt_pk_bf16_f32 v56, v70, v72
	v_cvt_pk_bf16_f32 v57, v71, v73
	v_cvt_pk_bf16_f32 v58, v74, v76
	v_cvt_pk_bf16_f32 v59, v75, v77
	v_cvt_pk_bf16_f32 v60, v182, v184
	v_cvt_pk_bf16_f32 v61, v183, v185
	v_cvt_pk_bf16_f32 v62, v186, v200
	v_cvt_pk_bf16_f32 v63, v187, v201
	v_add_f32_e32 v0, v14, v15
	s_setprio 1
	v_mfma_f32_32x32x16_bf16 v[16:31], v[136:139], v[48:51], v[16:31]
	v_add_f32_e32 v151, v151, v0
	v_mfma_f32_32x32x16_bf16 v[32:47], v[140:143], v[48:51], v[32:47]
	v_mfma_f32_32x32x16_bf16 v[16:31], v[108:111], v[56:59], v[16:31]
	v_mfma_f32_32x32x16_bf16 v[32:47], v[132:135], v[56:59], v[32:47]
	v_mfma_f32_32x32x16_bf16 v[16:31], v[100:103], v[52:55], v[16:31]
	v_mfma_f32_32x32x16_bf16 v[32:47], v[104:107], v[52:55], v[32:47]
	v_mfma_f32_32x32x16_bf16 v[16:31], v[96:99], v[60:63], v[16:31]
	v_mfma_f32_32x32x16_bf16 v[32:47], v[92:95], v[60:63], v[32:47]
	s_setprio 0

; #define MFMA(a, b, c) __builtin_amdgcn_mfma_f32_32x32x16_bf16((a), (b), (c), 0, 0, 0)
; template <int DK, int MODE> ...
;     ...
;     if (more) gload(ASC ? jt + 1 : jt - 1);
;     const int key0 = jt * 64;
;     const bool active = !CAUSAL || (key0 <= tq0 + 31);
;     if (active) {
;       f32x16 s0, s1;
;       const bf16_t* kb = sK + cur * 64 * LDK + l32 * LDK + h * 8;
;       bf16x8 kf0[NKS], kf1[NKS];
; #pragma unroll
;       for (int ks = 0; ks < NKS; ++ks) { kf0[ks] = *(const bf16x8*)(kb + ks * 16); kf1[ks] = *(const bf16x8*)(kb + 32 * LDK + ks * 16); }
;       if (MODE == 1) {
;         const float* fb = sF + cur * 64 + 4 * h;
; #pragma unroll
;         for (int g = 0; g < 4; ++g) {
;           const f32x4 f0 = *(const f32x4*)(fb + 8 * g), f1 = *(const f32x4*)(fb + 32 + 8 * g);
;           s0[4 * g] = f0.x; s0[4 * g + 1] = f0.y; s0[4 * g + 2] = f0.z; s0[4 * g + 3] = f0.w;
;           s1[4 * g] = f1.x; s1[4 * g + 1] = f1.y; s1[4 * g + 2] = f1.z; s1[4 * g + 3] = f1.w;
;         }
;       } else {
; #pragma unroll
;         for (int e = 0; e < 16; ++e) { s0[e] = 0.f; s1[e] = 0.f; }
;       }
;       __builtin_amdgcn_iglp_opt(0);
;       __builtin_amdgcn_s_setprio(1);
; #pragma unroll
;       for (int ks = 0; ks < NKS; ++ks) { s0 = MFMA(kf0[ks], qf[ks], s0); s1 = MFMA(kf1[ks], qf[ks], s1); }
;       __builtin_amdgcn_s_setprio(0);
;       const bf16_t* vb = sV + cur * 64 * 72 + l32 * 72 + h * 8;
;       bf16x8 vf0[4], vf1[4];
; #pragma unroll
;       for (int j = 0; j < 4; ++j) { vf0[j] = *(const bf16x8*)(vb + j * 16); vf1[j] = *(const bf16x8*)(vb + 32 * 72 + j * 16); }
;       __builtin_amdgcn_sched_barrier(0);
;       const bool need_mask = CAUSAL && (key0 + 63 >= tq0);
;       bf16x8 pf[4];
;       if (MODE != 2) {
;         if (need_mask) {
; #pragma unroll
;           for (int e = 0; e < 16; ++e) {
;             const int key = key0 + 8 * (e >> 2) + 4 * h + (e & 3);
;             if (key > qpos) s0[e] = -1e30f;
;             if (key + 32 > qpos) s1[e] = -1e30f;
;           }
.LBB0_526:
	v_lshl_add_u64 v[2:3], v[170:171], 0, s[46:47]
	global_load_dwordx4 v[88:91], v[2:3], off
	v_lshl_add_u64 v[2:3], v[168:169], 0, s[46:47]
	global_load_dwordx4 v[84:87], v[2:3], off
	v_lshl_add_u64 v[2:3], v[166:167], 0, s[46:47]
	global_load_dwordx4 v[10:13], v[2:3], off
	global_load_dwordx4 v[6:9], v[164:165], off
	s_nop 0
	global_load_dwordx4 v[2:5], v[162:163], off
	s_and_b32 s11, s10, 1
	s_cmp_gt_i32 s9, s8
	s_cbranch_scc1 .LBB0_525
	s_mul_i32 s12, s11, 0x3400
	v_add_u32_e32 v0, s12, v175
	ds_read_b128 v[48:51], v0 offset:6656
	ds_read_b128 v[52:55], v0
	ds_read_b128 v[92:95], v0 offset:32
	ds_read_b128 v[96:99], v0 offset:6688
	ds_read_b128 v[100:103], v0 offset:64
	ds_read_b128 v[104:107], v0 offset:6720
	ds_read_b128 v[108:111], v0 offset:96
	ds_read_b128 v[132:135], v0 offset:6752
	ds_read_b128 v[136:139], v0 offset:128
	ds_read_b128 v[140:143], v0 offset:6784
	ds_read_b128 v[176:179], v0 offset:160
	ds_read_b128 v[180:183], v0 offset:6816
	s_setprio 1
	s_setprio 0
	s_waitcnt lgkmcnt(10)
	v_mfma_f32_32x32x16_bf16 v[64:79], v[52:55], v[80:83], v[216:231]
	s_mul_i32 s12, s11, 0x2400
	v_add_u32_e32 v0, s12, v157
	v_mfma_f32_32x32x16_bf16 v[48:63], v[48:51], v[80:83], v[216:231]
	s_waitcnt lgkmcnt(9)
	v_mfma_f32_32x32x16_bf16 v[64:79], v[92:95], v[128:131], v[64:79]
	ds_read_b128 v[92:95], v0 offset:31328
	s_waitcnt lgkmcnt(9)
	v_mfma_f32_32x32x16_bf16 v[48:63], v[96:99], v[128:131], v[48:63]
	ds_read_b128 v[96:99], v0 offset:26720
	s_waitcnt lgkmcnt(9)
	v_mfma_f32_32x32x16_bf16 v[64:79], v[100:103], v[124:127], v[64:79]
	ds_read_b128 v[100:103], v0 offset:26688
	s_waitcnt lgkmcnt(9)
	v_mfma_f32_32x32x16_bf16 v[48:63], v[104:107], v[124:127], v[48:63]
	ds_read_b128 v[104:107], v0 offset:31296
	s_waitcnt lgkmcnt(9)
	v_mfma_f32_32x32x16_bf16 v[64:79], v[108:111], v[120:123], v[64:79]
	ds_read_b128 v[108:111], v0 offset:26656
	s_waitcnt lgkmcnt(9)
	v_mfma_f32_32x32x16_bf16 v[48:63], v[132:135], v[120:123], v[48:63]
	ds_read_b128 v[132:135], v0 offset:31264
	s_waitcnt lgkmcnt(9)
	v_mfma_f32_32x32x16_bf16 v[64:79], v[136:139], v[116:119], v[64:79]
	ds_read_b128 v[136:139], v0 offset:26624
	s_waitcnt lgkmcnt(9)
	v_mfma_f32_32x32x16_bf16 v[48:63], v[140:143], v[116:119], v[48:63]
	ds_read_b128 v[140:143], v0 offset:31232
	s_waitcnt lgkmcnt(9)
	v_mfma_f32_32x32x16_bf16 v[64:79], v[176:179], v[112:115], v[64:79]
	s_waitcnt lgkmcnt(8)
	v_mfma_f32_32x32x16_bf16 v[48:63], v[180:183], v[112:115], v[48:63]
	s_add_i32 s12, s9, 63
	s_cmp_lt_i32 s12, s1
	s_cbranch_scc1 .LBB0_529
	v_add_u32_e32 v0, s9, v149
	v_add_u32_e32 v14, 32, v0
	v_cmp_le_i32_e32 vcc, v14, v152
	v_add_u32_e32 v14, 33, v0
	s_nop 4
	v_cndmask_b32_e32 v48, v198, v48, vcc
	v_cmp_lt_i32_e32 vcc, v0, v152
	s_nop 1
	v_cndmask_b32_e32 v65, v198, v65, vcc
	v_cmp_le_i32_e32 vcc, v0, v152
	s_nop 1
	v_cndmask_b32_e32 v64, v198, v64, vcc
	v_cmp_le_i32_e32 vcc, v14, v152
	v_add_u32_e32 v14, 2, v0
	s_nop 0
	v_cndmask_b32_e32 v49, v198, v49, vcc
	v_cmp_le_i32_e32 vcc, v14, v152
	v_add_u32_e32 v14, 34, v0
	s_nop 0
	v_cndmask_b32_e32 v66, v198, v66, vcc
	v_cmp_le_i32_e32 vcc, v14, v152
	v_add_u32_e32 v14, 3, v0
	s_nop 0
	v_cndmask_b32_e32 v50, v198, v50, vcc
	v_cmp_le_i32_e32 vcc, v14, v152
	v_add_u32_e32 v14, 35, v0
	s_nop 0
	v_cndmask_b32_e32 v67, v198, v67, vcc
	v_cmp_le_i32_e32 vcc, v14, v152
	v_add_u32_e32 v14, 8, v0
	s_nop 0
	v_cndmask_b32_e32 v51, v198, v51, vcc
	v_cmp_le_i32_e32 vcc, v14, v152
	v_add_u32_e32 v14, 40, v0
	s_nop 0
	v_cndmask_b32_e32 v68, v198, v68, vcc
	v_cmp_le_i32_e32 vcc, v14, v152
	v_add_u32_e32 v14, 9, v0
	s_nop 0
	v_cndmask_b32_e32 v52, v198, v52, vcc
	v_cmp_le_i32_e32 vcc, v14, v152
	v_add_u32_e32 v14, 41, v0
	s_nop 0
	v_cndmask_b32_e32 v69, v198, v69, vcc
	v_cmp_le_i32_e32 vcc, v14, v152
	v_add_u32_e32 v14, 10, v0
	s_nop 0
	v_cndmask_b32_e32 v53, v198, v53, vcc
	v_cmp_le_i32_e32 vcc, v14, v152
	v_add_u32_e32 v14, 42, v0
	s_nop 0
	v_cndmask_b32_e32 v70, v198, v70, vcc
	v_cmp_le_i32_e32 vcc, v14, v152
	v_add_u32_e32 v14, 11, v0
	s_nop 0
	v_cndmask_b32_e32 v54, v198, v54, vcc
	v_cmp_le_i32_e32 vcc, v14, v152
	v_add_u32_e32 v14, 43, v0
	s_nop 0
	v_cndmask_b32_e32 v71, v198, v71, vcc
	v_cmp_le_i32_e32 vcc, v14, v152
	v_add_u32_e32 v14, 16, v0
	s_nop 0
	v_cndmask_b32_e32 v55, v198, v55, vcc
	v_cmp_le_i32_e32 vcc, v14, v152
	v_add_u32_e32 v14, 48, v0
	s_nop 0
	v_cndmask_b32_e32 v72, v198, v72, vcc
	v_cmp_le_i32_e32 vcc, v14, v152
	v_add_u32_e32 v14, 17, v0
	s_nop 0
	v_cndmask_b32_e32 v56, v198, v56, vcc
	v_cmp_le_i32_e32 vcc, v14, v152
	v_add_u32_e32 v14, 49, v0
	s_nop 0
	v_cndmask_b32_e32 v73, v198, v73, vcc
	v_cmp_le_i32_e32 vcc, v14, v152
	v_add_u32_e32 v14, 18, v0
	s_nop 0
	v_cndmask_b32_e32 v57, v198, v57, vcc
	v_cmp_le_i32_e32 vcc, v14, v152
	v_add_u32_e32 v14, 50, v0
	s_nop 0
	v_cndmask_b32_e32 v74, v198, v74, vcc
	v_cmp_le_i32_e32 vcc, v14, v152
	v_add_u32_e32 v14, 19, v0
	s_nop 0
	v_cndmask_b32_e32 v58, v198, v58, vcc
	v_cmp_le_i32_e32 vcc, v14, v152
	v_add_u32_e32 v14, 51, v0
	s_nop 0
	v_cndmask_b32_e32 v75, v198, v75, vcc
	v_cmp_le_i32_e32 vcc, v14, v152
	v_add_u32_e32 v14, 24, v0
	s_nop 0
	v_cndmask_b32_e32 v59, v198, v59, vcc
	v_cmp_le_i32_e32 vcc, v14, v152
	v_add_u32_e32 v14, 56, v0
	s_nop 0
	v_cndmask_b32_e32 v76, v198, v76, vcc
	v_cmp_le_i32_e32 vcc, v14, v152
	v_add_u32_e32 v14, 25, v0
	s_nop 0
	v_cndmask_b32_e32 v60, v198, v60, vcc
	v_cmp_le_i32_e32 vcc, v14, v152
	v_add_u32_e32 v14, 57, v0
	s_nop 0
	v_cndmask_b32_e32 v77, v198, v77, vcc
	v_cmp_le_i32_e32 vcc, v14, v152
	v_add_u32_e32 v14, 26, v0
	s_nop 0
	v_cndmask_b32_e32 v61, v198, v61, vcc
	v_cmp_le_i32_e32 vcc, v14, v152
	v_add_u32_e32 v14, 58, v0
	s_nop 0
	v_cndmask_b32_e32 v78, v198, v78, vcc
	v_cmp_le_i32_e32 vcc, v14, v152
	v_add_u32_e32 v14, 27, v0
	v_add_u32_e32 v0, 59, v0
	v_cndmask_b32_e32 v62, v198, v62, vcc
	v_cmp_le_i32_e32 vcc, v14, v152
	s_nop 1
	v_cndmask_b32_e32 v79, v198, v79, vcc
	v_cmp_le_i32_e32 vcc, v0, v152
	s_nop 1
	v_cndmask_b32_e32 v63, v198, v63, vcc
; template <int DK, int MODE> ...
;     ...
;         float mx = s0[0];
; #pragma unroll
;         for (int e = 1; e < 16; ++e) mx = fmaxf(mx, s0[e]);
; #pragma unroll
;         for (int e = 0; e < 16; ++e) mx = fmaxf(mx, s1[e]);
;         mx = fmaxf(mx, __shfl_xor(mx, 32));
;         if (__any(mx > m + 8.f)) {
;           const float mnew = fmaxf(m, mx);
;           const float alpha = __builtin_amdgcn_exp2f(m - mnew);
;           m = mnew; lsum *= alpha;
; #pragma unroll
;           for (int e = 0; e < 16; ++e) { o0[e] *= alpha; o1[e] *= alpha; }
;         }
.LBB0_529:
	s_nop 6
	v_max_f32_e32 v0, v65, v65
	v_max_f32_e32 v14, v64, v64
	v_max_f32_e32 v0, v14, v0
	v_max3_f32 v0, v0, v66, v67
	v_max3_f32 v0, v0, v68, v69
	v_max3_f32 v0, v0, v70, v71
	v_max3_f32 v0, v0, v72, v73
	v_max3_f32 v0, v0, v74, v75
	v_max3_f32 v0, v0, v76, v77
	v_max3_f32 v0, v0, v78, v79
	v_max3_f32 v0, v0, v48, v49
	v_max3_f32 v0, v0, v50, v51
	v_max3_f32 v0, v0, v52, v53
	v_mbcnt_hi_u32_b32 v14, -1, v189
	v_max3_f32 v0, v0, v54, v55
	v_and_b32_e32 v176, 64, v14
	v_max3_f32 v0, v0, v56, v57
	v_xor_b32_e32 v15, 32, v14
	v_add_u32_e32 v176, 64, v176
	v_max3_f32 v0, v0, v58, v59
	v_cmp_lt_i32_e32 vcc, v15, v176
	v_max3_f32 v0, v0, v60, v61
	v_max3_f32 v0, v0, v62, v63
	v_cndmask_b32_e32 v14, v14, v15, vcc
	v_lshlrev_b32_e32 v14, 2, v14
	ds_bpermute_b32 v14, v14, v0
	s_waitcnt lgkmcnt(0)
	v_max_f32_e32 v14, v14, v14
	v_max_f32_e32 v0, v0, v14
	s_cmp_eq_u32 s10, 0
	s_cbranch_scc1 .Lmla_rescale
	v_cmp_lt_f32_e32 vcc, 0x41000000, v0
	s_cbranch_vccz .LBB0_524
.Lmla_rescale:
	s_cmp_eq_u32 s10, 0
	s_cselect_b32 s12, 0xf149f2ca, 0
	v_max_f32_e32 v0, v0, v0
	v_max_f32_e32 v14, s12, v0
	v_sub_f32_e32 v216, v216, v14
	v_sub_f32_e32 v0, 0, v14
	v_min_f32_e32 v0, 0, v0
	v_exp_f32_e32 v0, v0
	v_sub_f32_e32 v155, 0, v216
	v_mov_b32_e32 v217, v216
	v_mov_b32_e32 v218, v216
	v_mov_b32_e32 v219, v216
	v_mov_b32_e32 v220, v216
	v_mov_b32_e32 v221, v216
	v_mov_b32_e32 v222, v216
	v_mov_b32_e32 v223, v216
	v_mov_b32_e32 v224, v216
	v_mov_b32_e32 v225, v216
	v_mov_b32_e32 v226, v216
	v_mov_b32_e32 v227, v216
	v_mov_b32_e32 v228, v216
	v_mov_b32_e32 v229, v216
	v_mov_b32_e32 v230, v216
	v_mov_b32_e32 v231, v216
	v_sub_f32_e32 v64, v64, v14
	v_sub_f32_e32 v65, v65, v14
	v_sub_f32_e32 v66, v66, v14
	v_sub_f32_e32 v67, v67, v14
	v_sub_f32_e32 v68, v68, v14
	v_sub_f32_e32 v69, v69, v14
	v_sub_f32_e32 v70, v70, v14
	v_sub_f32_e32 v71, v71, v14
	v_sub_f32_e32 v72, v72, v14
	v_sub_f32_e32 v73, v73, v14
	v_sub_f32_e32 v74, v74, v14
	v_sub_f32_e32 v75, v75, v14
	v_sub_f32_e32 v76, v76, v14
	v_sub_f32_e32 v77, v77, v14
	v_sub_f32_e32 v78, v78, v14
	v_sub_f32_e32 v79, v79, v14
	v_sub_f32_e32 v48, v48, v14
	v_sub_f32_e32 v49, v49, v14
	v_sub_f32_e32 v50, v50, v14
	v_sub_f32_e32 v51, v51, v14
	v_sub_f32_e32 v52, v52, v14
	v_sub_f32_e32 v53, v53, v14
	v_sub_f32_e32 v54, v54, v14
	v_sub_f32_e32 v55, v55, v14
	v_sub_f32_e32 v56, v56, v14
	v_sub_f32_e32 v57, v57, v14
	v_sub_f32_e32 v58, v58, v14
	v_sub_f32_e32 v59, v59, v14
	v_sub_f32_e32 v60, v60, v14
	v_sub_f32_e32 v61, v61, v14
	v_sub_f32_e32 v62, v62, v14
	v_sub_f32_e32 v63, v63, v14
	v_pk_mul_f32 v[30:31], v[30:31], v[0:1] op_sel_hi:[1,0]
	v_pk_mul_f32 v[28:29], v[28:29], v[0:1] op_sel_hi:[1,0]
	v_pk_mul_f32 v[26:27], v[26:27], v[0:1] op_sel_hi:[1,0]
	v_pk_mul_f32 v[24:25], v[24:25], v[0:1] op_sel_hi:[1,0]
	v_pk_mul_f32 v[22:23], v[22:23], v[0:1] op_sel_hi:[1,0]
	v_pk_mul_f32 v[20:21], v[20:21], v[0:1] op_sel_hi:[1,0]
	v_pk_mul_f32 v[18:19], v[18:19], v[0:1] op_sel_hi:[1,0]
	v_pk_mul_f32 v[16:17], v[16:17], v[0:1] op_sel_hi:[1,0]
	v_pk_mul_f32 v[46:47], v[46:47], v[0:1] op_sel_hi:[1,0]
	v_pk_mul_f32 v[44:45], v[44:45], v[0:1] op_sel_hi:[1,0]
	v_pk_mul_f32 v[42:43], v[42:43], v[0:1] op_sel_hi:[1,0]
	v_pk_mul_f32 v[40:41], v[40:41], v[0:1] op_sel_hi:[1,0]
	v_pk_mul_f32 v[38:39], v[38:39], v[0:1] op_sel_hi:[1,0]
	v_pk_mul_f32 v[36:37], v[36:37], v[0:1] op_sel_hi:[1,0]
	v_pk_mul_f32 v[34:35], v[34:35], v[0:1] op_sel_hi:[1,0]
	v_pk_mul_f32 v[32:33], v[32:33], v[0:1] op_sel_hi:[1,0]
	v_mul_f32_e32 v151, v151, v0
	s_branch .LBB0_524

; __global__ void __launch_bounds__(256, 2) mega(Params p_unused) {
	.amdhsa_kernel _Z4mega6Params
		.amdhsa_group_segment_fixed_size 74752
		.amdhsa_private_segment_fixed_size 0
		.amdhsa_kernarg_size 648
		.amdhsa_user_sgpr_count 2
		.amdhsa_user_sgpr_dispatch_ptr 0
		.amdhsa_user_sgpr_queue_ptr 0
		.amdhsa_user_sgpr_kernarg_segment_ptr 1
		.amdhsa_user_sgpr_dispatch_id 0
		.amdhsa_user_sgpr_kernarg_preload_length 0
		.amdhsa_user_sgpr_kernarg_preload_offset 0
		.amdhsa_user_sgpr_private_segment_size 0
		.amdhsa_uses_dynamic_stack 0
		.amdhsa_enable_private_segment 0
		.amdhsa_system_sgpr_workgroup_id_x 1
		.amdhsa_system_sgpr_workgroup_id_y 0
		.amdhsa_system_sgpr_workgroup_id_z 0
		.amdhsa_system_sgpr_workgroup_info 0
		.amdhsa_system_vgpr_workitem_id 2
		.amdhsa_next_free_vgpr 232
		.amdhsa_next_free_sgpr 100
		.amdhsa_accum_offset 232
		.amdhsa_reserve_vcc 1
		.amdhsa_float_round_mode_32 0
		.amdhsa_float_round_mode_16_64 0
		.amdhsa_float_denorm_mode_32 3
		.amdhsa_float_denorm_mode_16_64 3
		.amdhsa_dx10_clamp 1
		.amdhsa_ieee_mode 1
		.amdhsa_fp16_overflow 0
		.amdhsa_tg_split 0
		.amdhsa_exception_fp_ieee_invalid_op 0
		.amdhsa_exception_fp_denorm_src 0
		.amdhsa_exception_fp_ieee_div_zero 0
		.amdhsa_exception_fp_ieee_overflow 0
		.amdhsa_exception_fp_ieee_underflow 0
		.amdhsa_exception_fp_ieee_inexact 0
		.amdhsa_exception_int_div_zero 0
	.end_amdhsa_kernel

; __global__ void __launch_bounds__(256, 2) mega(Params p_unused) {
amdhsa.kernels:
  - .agpr_count:     0
    .args:
      - .offset:         0
        .size:           392
        .value_kind:     by_value
      - .offset:         392
        .size:           4
        .value_kind:     hidden_block_count_x
      - .offset:         396
        .size:           4
        .value_kind:     hidden_block_count_y
      - .offset:         400
        .size:           4
        .value_kind:     hidden_block_count_z
      - .offset:         404
        .size:           2
        .value_kind:     hidden_group_size_x
      - .offset:         406
        .size:           2
        .value_kind:     hidden_group_size_y
      - .offset:         408
        .size:           2
        .value_kind:     hidden_group_size_z
      - .offset:         410
        .size:           2
        .value_kind:     hidden_remainder_x
      - .offset:         412
        .size:           2
        .value_kind:     hidden_remainder_y
      - .offset:         414
        .size:           2
        .value_kind:     hidden_remainder_z
      - .offset:         432
        .size:           8
        .value_kind:     hidden_global_offset_x
      - .offset:         440
        .size:           8
        .value_kind:     hidden_global_offset_y
      - .offset:         448
        .size:           8
        .value_kind:     hidden_global_offset_z
      - .offset:         456
        .size:           2
        .value_kind:     hidden_grid_dims
      - .offset:         480
        .size:           8
        .value_kind:     hidden_multigrid_sync_arg
    .group_segment_fixed_size: 74752
    .kernarg_segment_align: 8
    .kernarg_segment_size: 648
    .language:       OpenCL C
    .language_version:
      - 2
      - 0
    .max_flat_workgroup_size: 256
    .name:           _Z4mega6Params
    .private_segment_fixed_size: 0
    .sgpr_count:     106
    .sgpr_spill_count: 74
    .symbol:         _Z4mega6Params.kd
    .uniform_work_group_size: 1
    .uses_dynamic_stack: false
    .vgpr_count:     232
    .vgpr_spill_count: 0
    .wavefront_size: 64
